# baseline (speedup 1.0000x reference)
; #define WAIT_V(n) asm volatile("s_waitcnt vmcnt(%0)" ::"n"(n) : "memory")
; #define SBAR() __builtin_amdgcn_sched_barrier(0)
; template <class Epi>
; DEV void gemm_phase_lerp(const u16* __restrict__ A2, const u16* __restrict__ Bt, const float* __restrict__ mu6, int nM, int nN, char* shm, const Epi& epi) {
;     ...
; #pragma unroll
;       for (int ks = 0; ks < 2; ++ks) {
;         bf16x8 At[8], Bf[4];
; #pragma unroll
;         for (int m = 0; m < 8; ++m) At[m] = *(const bf16x8*)(SA(cur) + la + m * 2048 + ks * 1024);
; #pragma unroll
;         for (int n = 0; n < 4; ++n) Bf[n] = *(const bf16x8*)(SB(cur) + lb + n * 2048 + ks * 1024);
;         __builtin_amdgcn_s_setprio(1);
; #pragma unroll
;         for (int m = 0; m < 8; ++m)
; #pragma unroll
;           for (int n = 0; n < 4; ++n)
;             acc[m][n] = __builtin_amdgcn_mfma_f32_16x16x32_bf16(Bf[n], At[m], acc[m][n], 0, 0, 0);
;         __builtin_amdgcn_s_setprio(0);
;         SBAR();
;       }
;       WAIT_V(0); __syncthreads();
;       if (do_stage) BLEND(cur ^ 1, m0, m1);
;       __syncthreads();
.LBB0_534:
	v_add_u32_e32 v146, s1, v145
	v_add_u32_e32 v202, s1, v151
	ds_read_b128 v[152:155], v146
	ds_read_b128 v[156:159], v146 offset:2048
	ds_read_b128 v[160:163], v146 offset:4096
	ds_read_b128 v[166:169], v146 offset:6144
	ds_read_b128 v[170:173], v146 offset:8192
	ds_read_b128 v[174:177], v146 offset:10240
	ds_read_b128 v[178:181], v146 offset:12288
	ds_read_b128 v[182:185], v146 offset:14336
	ds_read_b128 v[186:189], v202 offset:32768
	ds_read_b128 v[190:193], v202 offset:34816
	ds_read_b128 v[194:197], v202 offset:36864
	ds_read_b128 v[198:201], v202 offset:38912
	s_setprio 1
	s_waitcnt lgkmcnt(0)
	v_mfma_f32_16x16x32_bf16 v[124:127], v[186:189], v[152:155], v[124:127]
	v_mfma_f32_16x16x32_bf16 v[120:123], v[190:193], v[152:155], v[120:123]
	v_mfma_f32_16x16x32_bf16 v[116:119], v[194:197], v[152:155], v[116:119]
	v_mfma_f32_16x16x32_bf16 v[112:115], v[198:201], v[152:155], v[112:115]
	v_mfma_f32_16x16x32_bf16 v[108:111], v[186:189], v[156:159], v[108:111]
	v_mfma_f32_16x16x32_bf16 v[104:107], v[190:193], v[156:159], v[104:107]
	v_mfma_f32_16x16x32_bf16 v[100:103], v[194:197], v[156:159], v[100:103]
	v_mfma_f32_16x16x32_bf16 v[96:99], v[198:201], v[156:159], v[96:99]
	v_mfma_f32_16x16x32_bf16 v[92:95], v[186:189], v[160:163], v[92:95]
	v_mfma_f32_16x16x32_bf16 v[88:91], v[190:193], v[160:163], v[88:91]
	v_mfma_f32_16x16x32_bf16 v[84:87], v[194:197], v[160:163], v[84:87]
	v_mfma_f32_16x16x32_bf16 v[80:83], v[198:201], v[160:163], v[80:83]
	v_mfma_f32_16x16x32_bf16 v[76:79], v[186:189], v[166:169], v[76:79]
	v_mfma_f32_16x16x32_bf16 v[72:75], v[190:193], v[166:169], v[72:75]
	v_mfma_f32_16x16x32_bf16 v[68:71], v[194:197], v[166:169], v[68:71]
	v_mfma_f32_16x16x32_bf16 v[64:67], v[198:201], v[166:169], v[64:67]
	v_mfma_f32_16x16x32_bf16 v[60:63], v[186:189], v[170:173], v[60:63]
	v_mfma_f32_16x16x32_bf16 v[56:59], v[190:193], v[170:173], v[56:59]
	v_mfma_f32_16x16x32_bf16 v[52:55], v[194:197], v[170:173], v[52:55]
	v_mfma_f32_16x16x32_bf16 v[48:51], v[198:201], v[170:173], v[48:51]
	v_mfma_f32_16x16x32_bf16 v[44:47], v[186:189], v[174:177], v[44:47]
	v_mfma_f32_16x16x32_bf16 v[40:43], v[190:193], v[174:177], v[40:43]
	v_mfma_f32_16x16x32_bf16 v[36:39], v[194:197], v[174:177], v[36:39]
	v_mfma_f32_16x16x32_bf16 v[32:35], v[198:201], v[174:177], v[32:35]
	v_mfma_f32_16x16x32_bf16 v[28:31], v[186:189], v[178:181], v[28:31]
	v_mfma_f32_16x16x32_bf16 v[24:27], v[190:193], v[178:181], v[24:27]
	v_mfma_f32_16x16x32_bf16 v[20:23], v[194:197], v[178:181], v[20:23]
	v_mfma_f32_16x16x32_bf16 v[16:19], v[198:201], v[178:181], v[16:19]
	v_mfma_f32_16x16x32_bf16 v[12:15], v[186:189], v[182:185], v[12:15]
	v_mfma_f32_16x16x32_bf16 v[8:11], v[190:193], v[182:185], v[8:11]
	v_mfma_f32_16x16x32_bf16 v[4:7], v[194:197], v[182:185], v[4:7]
	v_mfma_f32_16x16x32_bf16 v[0:3], v[198:201], v[182:185], v[0:3]
	s_setprio 0
	ds_read_b128 v[152:155], v146 offset:1024
	ds_read_b128 v[156:159], v146 offset:3072
	ds_read_b128 v[160:163], v146 offset:5120
	ds_read_b128 v[166:169], v146 offset:7168
	ds_read_b128 v[170:173], v146 offset:9216
	ds_read_b128 v[174:177], v146 offset:11264
	ds_read_b128 v[178:181], v146 offset:13312
	ds_read_b128 v[182:185], v146 offset:15360
	ds_read_b128 v[186:189], v202 offset:33792
	ds_read_b128 v[190:193], v202 offset:35840
	ds_read_b128 v[194:197], v202 offset:37888
	ds_read_b128 v[198:201], v202 offset:39936
	s_setprio 1
	s_waitcnt lgkmcnt(0)
	v_mfma_f32_16x16x32_bf16 v[124:127], v[186:189], v[152:155], v[124:127]
	v_mfma_f32_16x16x32_bf16 v[120:123], v[190:193], v[152:155], v[120:123]
	v_mfma_f32_16x16x32_bf16 v[116:119], v[194:197], v[152:155], v[116:119]
	v_mfma_f32_16x16x32_bf16 v[112:115], v[198:201], v[152:155], v[112:115]
	v_mfma_f32_16x16x32_bf16 v[108:111], v[186:189], v[156:159], v[108:111]
	v_mfma_f32_16x16x32_bf16 v[104:107], v[190:193], v[156:159], v[104:107]
	v_mfma_f32_16x16x32_bf16 v[100:103], v[194:197], v[156:159], v[100:103]
	v_mfma_f32_16x16x32_bf16 v[96:99], v[198:201], v[156:159], v[96:99]
	v_mfma_f32_16x16x32_bf16 v[92:95], v[186:189], v[160:163], v[92:95]
	v_mfma_f32_16x16x32_bf16 v[88:91], v[190:193], v[160:163], v[88:91]
	v_mfma_f32_16x16x32_bf16 v[84:87], v[194:197], v[160:163], v[84:87]
	v_mfma_f32_16x16x32_bf16 v[80:83], v[198:201], v[160:163], v[80:83]
	v_mfma_f32_16x16x32_bf16 v[76:79], v[186:189], v[166:169], v[76:79]
	v_mfma_f32_16x16x32_bf16 v[72:75], v[190:193], v[166:169], v[72:75]
	v_mfma_f32_16x16x32_bf16 v[68:71], v[194:197], v[166:169], v[68:71]
	v_mfma_f32_16x16x32_bf16 v[64:67], v[198:201], v[166:169], v[64:67]
	v_mfma_f32_16x16x32_bf16 v[60:63], v[186:189], v[170:173], v[60:63]
	v_mfma_f32_16x16x32_bf16 v[56:59], v[190:193], v[170:173], v[56:59]
	v_mfma_f32_16x16x32_bf16 v[52:55], v[194:197], v[170:173], v[52:55]
	v_mfma_f32_16x16x32_bf16 v[48:51], v[198:201], v[170:173], v[48:51]
	v_mfma_f32_16x16x32_bf16 v[44:47], v[186:189], v[174:177], v[44:47]
	v_mfma_f32_16x16x32_bf16 v[40:43], v[190:193], v[174:177], v[40:43]
	v_mfma_f32_16x16x32_bf16 v[36:39], v[194:197], v[174:177], v[36:39]
	v_mfma_f32_16x16x32_bf16 v[32:35], v[198:201], v[174:177], v[32:35]
	v_mfma_f32_16x16x32_bf16 v[28:31], v[186:189], v[178:181], v[28:31]
	v_mfma_f32_16x16x32_bf16 v[24:27], v[190:193], v[178:181], v[24:27]
	v_mfma_f32_16x16x32_bf16 v[20:23], v[194:197], v[178:181], v[20:23]
	v_mfma_f32_16x16x32_bf16 v[16:19], v[198:201], v[178:181], v[16:19]
	v_mfma_f32_16x16x32_bf16 v[12:15], v[186:189], v[182:185], v[12:15]
	v_mfma_f32_16x16x32_bf16 v[8:11], v[190:193], v[182:185], v[8:11]
	v_mfma_f32_16x16x32_bf16 v[4:7], v[194:197], v[182:185], v[4:7]
	v_mfma_f32_16x16x32_bf16 v[0:3], v[198:201], v[182:185], v[0:3]
	s_setprio 0
	s_waitcnt vmcnt(0)
	s_andn2_b64 vcc, exec, s[34:35]
	s_waitcnt vmcnt(0)
	s_cbranch_vccnz .LBB0_529
; template <class Epi>
; DEV void gemm_phase_lerp(const u16* __restrict__ A2, const u16* __restrict__ Bt, const float* __restrict__ mu6, int nM, int nN, char* shm, const Epi& epi) {
;     ...
;       if (do_stage) BLEND(cur ^ 1, m0, m1);
;       __syncthreads();
;       cur ^= 1;
	s_xor_b32 s1, s1, 0x10000
	v_add_u32_e32 v146, s1, v143
	v_add_u32_e32 v160, s71, v141
	ds_read_b128 v[152:155], v146
	ds_read_b128 v[156:159], v160
	s_waitcnt lgkmcnt(1)
	v_lshlrev_b32_e32 v161, 16, v152
	v_and_b32_e32 v152, 0xffff0000, v152
	v_lshlrev_b32_e32 v162, 16, v153
	v_and_b32_e32 v153, 0xffff0000, v153
	v_lshlrev_b32_e32 v163, 16, v154
	v_and_b32_e32 v154, 0xffff0000, v154
	v_lshlrev_b32_e32 v166, 16, v155
	v_and_b32_e32 v155, 0xffff0000, v155
	s_waitcnt lgkmcnt(0)
	v_lshlrev_b32_e32 v167, 16, v156
	v_and_b32_e32 v156, 0xffff0000, v156
	v_lshlrev_b32_e32 v168, 16, v157
	v_and_b32_e32 v157, 0xffff0000, v157
	v_lshlrev_b32_e32 v169, 16, v158
	v_and_b32_e32 v158, 0xffff0000, v158
	v_lshlrev_b32_e32 v170, 16, v159
	v_and_b32_e32 v159, 0xffff0000, v159
	v_fmac_f32_e32 v152, v156, v129
	v_fmac_f32_e32 v154, v158, v133
	v_fmac_f32_e32 v153, v157, v131
	v_fmac_f32_e32 v155, v159, v135
	v_fmac_f32_e32 v161, v167, v128
	v_fmac_f32_e32 v163, v169, v132
	v_fmac_f32_e32 v162, v168, v130
	v_fmac_f32_e32 v166, v170, v134
	v_cvt_pk_bf16_f32 v152, v161, v152
	v_cvt_pk_bf16_f32 v153, v162, v153
	v_cvt_pk_bf16_f32 v154, v163, v154
	v_cvt_pk_bf16_f32 v155, v166, v155
	ds_write_b128 v146, v[152:155]
	ds_read_b128 v[156:159], v146 offset:8192
	ds_read_b128 v[152:155], v160 offset:8192
	s_waitcnt lgkmcnt(1)
	v_lshlrev_b32_e32 v161, 16, v156
	v_and_b32_e32 v156, 0xffff0000, v156
	v_lshlrev_b32_e32 v162, 16, v157
	v_and_b32_e32 v157, 0xffff0000, v157
	v_lshlrev_b32_e32 v163, 16, v158
	v_and_b32_e32 v158, 0xffff0000, v158
	v_lshlrev_b32_e32 v166, 16, v159
	v_and_b32_e32 v159, 0xffff0000, v159
	s_waitcnt lgkmcnt(0)
	v_lshlrev_b32_e32 v167, 16, v152
	v_and_b32_e32 v152, 0xffff0000, v152
	v_lshlrev_b32_e32 v168, 16, v153
	v_and_b32_e32 v153, 0xffff0000, v153
	v_lshlrev_b32_e32 v169, 16, v154
	v_and_b32_e32 v154, 0xffff0000, v154
	v_lshlrev_b32_e32 v170, 16, v155
	v_and_b32_e32 v155, 0xffff0000, v155
	v_fmac_f32_e32 v161, v167, v128
	v_fmac_f32_e32 v163, v169, v132
	v_fmac_f32_e32 v156, v152, v129
	v_fmac_f32_e32 v158, v154, v133
	v_fmac_f32_e32 v162, v168, v130
	v_fmac_f32_e32 v166, v170, v134
	v_fmac_f32_e32 v157, v153, v131
	v_fmac_f32_e32 v159, v155, v135
	v_cvt_pk_bf16_f32 v152, v161, v156
	v_cvt_pk_bf16_f32 v153, v162, v157
	v_cvt_pk_bf16_f32 v154, v163, v158
	v_cvt_pk_bf16_f32 v155, v166, v159
	ds_write_b128 v146, v[152:155] offset:8192
	ds_read_b128 v[156:159], v146 offset:16384
	ds_read_b128 v[152:155], v160 offset:16384
	s_waitcnt lgkmcnt(1)
	v_lshlrev_b32_e32 v161, 16, v156
	v_and_b32_e32 v156, 0xffff0000, v156
	v_lshlrev_b32_e32 v162, 16, v157
	v_and_b32_e32 v157, 0xffff0000, v157
	v_lshlrev_b32_e32 v163, 16, v158
	v_and_b32_e32 v158, 0xffff0000, v158
	v_lshlrev_b32_e32 v166, 16, v159
	v_and_b32_e32 v159, 0xffff0000, v159
	s_waitcnt lgkmcnt(0)
	v_lshlrev_b32_e32 v167, 16, v152
	v_and_b32_e32 v152, 0xffff0000, v152
	v_lshlrev_b32_e32 v168, 16, v153
	v_and_b32_e32 v153, 0xffff0000, v153
	v_lshlrev_b32_e32 v169, 16, v154
	v_and_b32_e32 v154, 0xffff0000, v154
	v_lshlrev_b32_e32 v170, 16, v155
	v_and_b32_e32 v155, 0xffff0000, v155
	v_fmac_f32_e32 v161, v167, v128
	v_fmac_f32_e32 v163, v169, v132
	v_fmac_f32_e32 v156, v152, v129
	v_fmac_f32_e32 v158, v154, v133
	v_fmac_f32_e32 v162, v168, v130
	v_fmac_f32_e32 v166, v170, v134
	v_fmac_f32_e32 v157, v153, v131
	v_fmac_f32_e32 v159, v155, v135
	v_cvt_pk_bf16_f32 v152, v161, v156
	v_cvt_pk_bf16_f32 v153, v162, v157
	v_cvt_pk_bf16_f32 v154, v163, v158
	v_cvt_pk_bf16_f32 v155, v166, v159
	ds_write_b128 v146, v[152:155] offset:16384
	ds_read_b128 v[156:159], v146 offset:24576
	ds_read_b128 v[152:155], v160 offset:24576
	s_waitcnt lgkmcnt(1)
	v_lshlrev_b32_e32 v160, 16, v156
	v_and_b32_e32 v156, 0xffff0000, v156
	v_lshlrev_b32_e32 v161, 16, v157
	v_and_b32_e32 v157, 0xffff0000, v157
	v_lshlrev_b32_e32 v162, 16, v158
	v_and_b32_e32 v158, 0xffff0000, v158
	v_lshlrev_b32_e32 v163, 16, v159
	v_and_b32_e32 v159, 0xffff0000, v159
	s_waitcnt lgkmcnt(0)
	v_lshlrev_b32_e32 v166, 16, v152
	v_and_b32_e32 v152, 0xffff0000, v152
	v_lshlrev_b32_e32 v167, 16, v153
	v_and_b32_e32 v153, 0xffff0000, v153
	v_lshlrev_b32_e32 v168, 16, v154
	v_and_b32_e32 v154, 0xffff0000, v154
	v_lshlrev_b32_e32 v169, 16, v155
	v_and_b32_e32 v155, 0xffff0000, v155
	v_fmac_f32_e32 v160, v166, v128
	v_fmac_f32_e32 v162, v168, v132
	v_fmac_f32_e32 v156, v152, v129
	v_fmac_f32_e32 v158, v154, v133
	v_fmac_f32_e32 v161, v167, v130
	v_fmac_f32_e32 v163, v169, v134
	v_fmac_f32_e32 v157, v153, v131
	v_fmac_f32_e32 v159, v155, v135
	v_cvt_pk_bf16_f32 v128, v160, v156
	v_cvt_pk_bf16_f32 v129, v161, v157
	v_cvt_pk_bf16_f32 v130, v162, v158
	v_cvt_pk_bf16_f32 v131, v163, v159
	ds_write_b128 v146, v[128:131] offset:24576
	s_branch .LBB0_529
